# HGRN pass-2 chunk loop: top-of-loop wait counted (vmcnt(4)) so the previous chunk's output stores stay in flight; full wait moved to the preheader
# speedup vs baseline: 1.0063x; 1.0027x over previous
; #define MFMA32(a, b, c) __builtin_amdgcn_mfma_f32_32x32x16_bf16((a), (b), (c), 0, 0, 0)
; DI u32 pack2bf(float lo, float hi) { f32x2 v = {lo, hi}; return __builtin_bit_cast(u32, __builtin_convertvector(v, bf2_t)); }
; DI int crow(int i, int h) { return (i & 3) + 8 * (i >> 2) + 4 * h; }
; DI bf16x8 cat44(s16x4 lo, s16x4 hi) { return __builtin_shufflevector(lo, hi, 0, 1, 2, 3, 4, 5, 6, 7); }
; template <int PASS>
; DI void hgrn_unit(const Params& p, int layer, int unit, char* smem) {
;     ...
;   for (int c = c_begin; c < c_end; ++c) {
;     const int t0 = chunk_t0(c);
;     asm volatile("s_waitcnt vmcnt(0)" ::: "memory");
;     ...
;         bf16x8 a = *(const bf16x8*)(sKm + r * HS + ks * 16 + 8 * h);
;         bf16x8 b = *(const bf16x8*)(sQm + r * HS + ks * 16 + 8 * h);
;         at = MFMA32(a, b, at);
;       }
; #pragma unroll
;       for (int i = 0; i < 16; ++i) if (crow(i, h) > r) at[i] = 0.f;
; #pragma unroll
;       for (int db = 0; db < 4; ++db)
; #pragma unroll
;         for (int s2 = 0; s2 < 2; ++s2) {
;           bf16x8 a = pack8(S[db], s2);
;           s16x4 lo = *(const s16x4*)(sQb + r * HS + db * 32 + s2 * 16 + 4 * h);
;           s16x4 hi = *(const s16x4*)(sQb + r * HS + db * 32 + s2 * 16 + 8 + 4 * h);
;           oT = MFMA32(a, cat44(lo, hi), oT);
;         }
; #pragma unroll
;       for (int ks = 0; ks < 2; ++ks) {
;         s16x4 lo = *(const s16x4*)(sVt + (32 * w + r) * VS + 16 * ks + 4 * h);
;         s16x4 hi = *(const s16x4*)(sVt + (32 * w + r) * VS + 16 * ks + 8 + 4 * h);
;         oT = MFMA32(cat44(lo, hi), pack8(at, ks), oT);
;       }
;       int tok = dir ? t0 + 31 - r : t0 + r;
; #pragma unroll
;       for (int g = 0; g < 4; ++g) {
;         u32x2 pk = {pack2bf(oT[4 * g], oT[4 * g + 1]), pack2bf(oT[4 * g + 2], oT[4 * g + 3])};
;         *(u32x2*)(od + (size_t)tok * 512 + hd * 128 + 32 * w + 8 * g + 4 * h) = pk;
.LBB0_602:
	s_and_b64 s[8:9], s[0:1], exec
	s_mov_b32 s8, 0xd800000
	s_cselect_b32 s8, s8, 0x10800000
	s_add_u32 s8, s70, s8
	s_addc_u32 s9, s71, 0
	s_add_i32 s79, s76, 0x80
	s_add_u32 s6, s6, s60
	s_addc_u32 s7, s7, 0
	v_lshlrev_b32_e32 v64, 1, v98
	v_mov_b32_e32 v65, v97
	s_add_u32 s8, s8, s4
	v_and_b32_e32 v66, 31, v100
	v_lshl_add_u64 v[98:99], s[6:7], 0, v[64:65]
	s_addc_u32 s9, s9, s5
	s_lshl_b32 s6, s12, 5
	v_or_b32_e32 v65, s6, v66
	s_movk_i32 s7, 0x50
	v_mul_lo_u32 v65, v65, s7
	s_ashr_i32 s7, s6, 31
	s_lshl_b64 s[6:7], s[6:7], 1
	s_add_u32 s6, s8, s6
	s_movk_i32 s8, 0x880
	v_and_b32_e32 v67, 0x7f, v100
	s_movk_i32 s4, 0x80
	v_mul_lo_u32 v68, v117, s8
	v_cmp_gt_u32_e64 s[42:43], s4, v100
	s_movk_i32 s4, 0x7f
	v_mul_u32_u24_e32 v64, 40, v67
	v_lshlrev_b32_e32 v105, 2, v67
	s_addc_u32 s7, s9, s7
	v_or_b32_e32 v67, v68, v67
	v_cmp_lt_u32_e64 s[4:5], s4, v100
	v_lshl_add_u64 v[100:101], v[96:97], 1, s[6:7]
	v_cmp_eq_u32_e64 s[6:7], 1, v117
	v_lshlrev_b32_e32 v117, 1, v67
	v_or_b32_e32 v67, 2, v96
	v_cmp_gt_u32_e64 s[12:13], v67, v66
	v_or_b32_e32 v67, 3, v96
	v_cmp_gt_u32_e64 s[14:15], v67, v66
	v_or_b32_e32 v67, 8, v96
	v_cmp_gt_u32_e64 s[16:17], v67, v66
	v_or_b32_e32 v67, 9, v96
	v_cmp_gt_u32_e64 s[18:19], v67, v66
	v_or_b32_e32 v67, 10, v96
	v_cmp_gt_u32_e64 s[20:21], v67, v66
	v_or_b32_e32 v67, 11, v96
	v_cmp_gt_u32_e64 s[22:23], v67, v66
	v_or_b32_e32 v67, 16, v96
	v_cmp_gt_u32_e64 s[24:25], v67, v66
	v_or_b32_e32 v67, 17, v96
	v_cmp_gt_u32_e64 s[26:27], v67, v66
	v_or_b32_e32 v67, 18, v96
	v_cmp_gt_u32_e64 s[28:29], v67, v66
	v_or_b32_e32 v67, 19, v96
	v_lshlrev_b32_e32 v64, 1, v64
	v_cmp_gt_u32_e64 s[30:31], v67, v66
	v_or_b32_e32 v67, 24, v96
	v_lshl_add_u32 v104, v115, 1, v64
	v_mul_u32_u24_e32 v64, 0x88, v66
	v_cmp_gt_u32_e64 s[34:35], v67, v66
	v_or_b32_e32 v67, 25, v96
	v_lshlrev_b32_e32 v64, 1, v64
	v_lshlrev_b32_e32 v106, 4, v118
	v_cmp_gt_u32_e64 s[36:37], v67, v66
	v_or_b32_e32 v67, 26, v96
	v_lshlrev_b32_e32 v68, 1, v96
	v_mov_b32_e32 v103, v97
	v_add_u32_e32 v107, v64, v106
	v_cmp_gt_u32_e64 s[8:9], v96, v66
	v_cmp_lt_u32_e64 s[10:11], v96, v66
	v_cmp_gt_u32_e64 s[38:39], v67, v66
	v_or_b32_e32 v67, 27, v96
	v_add_u32_e32 v96, v64, v68
	v_mul_u32_u24_e32 v64, 0x50, v66
	s_sub_i32 s60, s74, s76
	s_mov_b32 s78, 0
	v_add_u32_e32 v115, v65, v106
	v_lshl_add_u32 v116, v116, 1, s77
	v_cmp_gt_u32_e64 s[40:41], v67, v66
	v_add_u32_e32 v118, v65, v68
	v_or_b32_e32 v119, s67, v66
	s_add_i32 s60, s60, -2
	v_lshlrev_b64 v[102:103], 1, v[102:103]
	v_add_u32_e32 v120, v106, v64
	s_waitcnt vmcnt(0)
	s_branch .LBB0_604

; DI float h2f(u16 b) { return (float)__builtin_bit_cast(_Float16, b); }
; template <int PASS>
; DI void hgrn_unit(const Params& p, int layer, int unit, char* smem) {
;     ...
;   auto gl = [&](int c) {
;     const int t0 = chunk_t0(c);
;     const int row8 = lane >> 3, ch = lane & 7;
; #pragma unroll
;     for (int i = 0; i < 4; ++i) {
;       int j = 8 * i + row8;
;       size_t off = (size_t)(dir ? t0 + 31 - j : t0 + j) * 512 + dcol + ch * 8;
;       __builtin_amdgcn_global_load_lds((const unsigned*)(gg + off), (unsigned*)(rawW + i * 1024 + lane * 16), 16, 0, 0);
;     }
; #pragma unroll
;     for (int i = 0; i < 2; ++i) {
;       int j = half * 16 + 8 * i + row8;
;       size_t off = (size_t)(dir ? t0 + 31 - j : t0 + j) * 512 + dcol + ch * 8;
;       if (PASS == 2) __builtin_amdgcn_global_load_lds((const unsigned*)(gq + off), (unsigned*)(rawW + 4096 + i * 1024 + lane * 16), 16, 0, 0);
;       __builtin_amdgcn_global_load_lds((const unsigned*)(gv + off), (unsigned*)(rawW + 6144 + i * 1024 + lane * 16), 16, 0, 0);
;     }
;   };
;     ...
;   for (int c = c_begin; c < c_end; ++c) {
;     const int t0 = chunk_t0(c);
;     asm volatile("s_waitcnt vmcnt(0)" ::: "memory");
;     const u16* rG = (const u16*)rawW; const u16* rQ = rG + 2048; const u16* rV = rG + 3072;
;     float tot0 = 0.f, tot1 = 0.f, g16;
;     float gval[16]; u16 qraw[16], vraw[16];
; #pragma unroll
;     for (int j = 0; j < 32; ++j) {
;       float g = h2f(rG[j * 64 + lane]);
;       if (j < 16) tot0 += g; else tot1 += g;
;       if (j == 16) g16 = g;
;       if ((j >> 4) == half) gval[j & 15] = g;
;     }
; #pragma unroll
;     for (int jj = 0; jj < 16; ++jj) { if (PASS == 2) qraw[jj] = rQ[jj * 64 + lane]; vraw[jj] = rV[jj * 64 + lane]; }
;     asm volatile("s_waitcnt lgkmcnt(0)" ::: "memory");
;     __builtin_amdgcn_sched_barrier(0);
;     if (c + 1 < c_end) gl(c + 1);
.LBB0_604:
	s_waitcnt vmcnt(4)
	ds_read_u16 v168, v116 offset:47104
	ds_read_u16 v167, v116 offset:47232
	ds_read_u16 v166, v116 offset:47360
	ds_read_u16 v165, v116 offset:47488
	ds_read_u16 v164, v116 offset:47616
	ds_read_u16 v163, v116 offset:47744
	ds_read_u16 v162, v116 offset:47872
	ds_read_u16 v161, v116 offset:48000
	ds_read_u16 v160, v116 offset:48128
	ds_read_u16 v159, v116 offset:48256
	ds_read_u16 v158, v116 offset:48384
	ds_read_u16 v157, v116 offset:48512
	ds_read_u16 v156, v116 offset:48640
	ds_read_u16 v155, v116 offset:48768
	ds_read_u16 v154, v116 offset:48896
	ds_read_u16 v153, v116 offset:49024
	ds_read_u16 v152, v116 offset:49152
	ds_read_u16 v151, v116 offset:49280
	ds_read_u16 v150, v116 offset:49408
	ds_read_u16 v149, v116 offset:49536
	ds_read_u16 v148, v116 offset:49664
	ds_read_u16 v147, v116 offset:49792
	ds_read_u16 v146, v116 offset:49920
	ds_read_u16 v145, v116 offset:50048
	ds_read_u16 v144, v116 offset:50176
	ds_read_u16 v94, v116 offset:50304
	ds_read_u16 v93, v116 offset:50432
	ds_read_u16 v92, v116 offset:50560
	ds_read_u16 v71, v116 offset:50688
	ds_read_u16 v66, v116 offset:50816
	ds_read_u16 v65, v116 offset:50944
	ds_read_u16 v64, v116 offset:51072
	ds_read_u16 v90, v116 offset:51200
	ds_read_u16 v72, v116 offset:51328
	ds_read_u16 v89, v116 offset:51456
	ds_read_u16 v73, v116 offset:51584
	ds_read_u16 v88, v116 offset:51712
	ds_read_u16 v74, v116 offset:51840
	ds_read_u16 v87, v116 offset:51968
	ds_read_u16 v75, v116 offset:52096
	ds_read_u16 v67, v116 offset:53248
	ds_read_u16 v76, v116 offset:53376
	ds_read_u16 v68, v116 offset:53504
	ds_read_u16 v77, v116 offset:53632
	ds_read_u16 v69, v116 offset:53760
	ds_read_u16 v78, v116 offset:53888
	ds_read_u16 v70, v116 offset:54016
	ds_read_u16 v91, v116 offset:54144
	ds_read_u16 v86, v116 offset:52224
	ds_read_u16 v85, v116 offset:52352
	ds_read_u16 v84, v116 offset:52480
	ds_read_u16 v83, v116 offset:52608
	ds_read_u16 v82, v116 offset:52736
	ds_read_u16 v81, v116 offset:52864
	ds_read_u16 v80, v116 offset:52992
	ds_read_u16 v79, v116 offset:53120
	ds_read_u16 v95, v116 offset:54272
	ds_read_u16 v140, v116 offset:54400
	ds_read_u16 v137, v116 offset:54528
	ds_read_u16 v141, v116 offset:54656
	ds_read_u16 v138, v116 offset:54784
	ds_read_u16 v142, v116 offset:54912
	ds_read_u16 v139, v116 offset:55040
	ds_read_u16 v143, v116 offset:55168
	s_waitcnt lgkmcnt(0)
	s_add_i32 s80, s76, s78
	s_add_i32 s74, s80, 1
	s_cmp_lt_u32 s74, s79
	s_cselect_b64 s[92:93], -1, 0
	s_cmp_ge_u32 s74, s79
	s_cbranch_scc1 .LBB0_606
	s_and_b64 s[82:83], s[0:1], exec
	s_cselect_b32 s74, s74, s60
	s_lshl_b32 s74, s74, 5
	s_add_i32 s74, s74, s67
	s_or_b32 s75, s74, 31
	v_sub_u32_e32 v169, s75, v108
	v_or_b32_e32 v170, s74, v108
	v_cndmask_b32_e64 v170, v169, v170, s[0:1]
	v_add_u32_e32 v169, s77, v109
	v_ashrrev_i32_e32 v171, 31, v170
	v_add_u32_e32 v172, 0xb800, v169
	v_lshlrev_b64 v[170:171], 10, v[170:171]
	v_readfirstlane_b32 s81, v172
	v_lshl_add_u64 v[170:171], v[98:99], 0, v[170:171]
	s_mov_b32 m0, s81
	v_add_u32_e32 v172, 0xbc00, v169
	global_load_lds_dwordx4 v[170:171], off
	v_sub_u32_e32 v170, s75, v110
	v_or_b32_e32 v171, s74, v110
	v_cndmask_b32_e64 v170, v170, v171, s[0:1]
	v_ashrrev_i32_e32 v171, 31, v170
	v_lshlrev_b64 v[170:171], 10, v[170:171]
	v_readfirstlane_b32 s81, v172
	v_lshl_add_u64 v[170:171], v[98:99], 0, v[170:171]
	s_mov_b32 m0, s81
	v_add_u32_e32 v172, 0xc000, v169
	global_load_lds_dwordx4 v[170:171], off
	v_sub_u32_e32 v170, s75, v111
	v_or_b32_e32 v171, s74, v111
	v_cndmask_b32_e64 v170, v170, v171, s[0:1]
	v_ashrrev_i32_e32 v171, 31, v170
	v_lshlrev_b64 v[170:171], 10, v[170:171]
	v_readfirstlane_b32 s81, v172
	v_lshl_add_u64 v[170:171], v[98:99], 0, v[170:171]
	s_mov_b32 m0, s81
	v_add_u32_e32 v172, 0xc400, v169
	global_load_lds_dwordx4 v[170:171], off
	v_sub_u32_e32 v170, s75, v112
	v_or_b32_e32 v171, s74, v112
	v_cndmask_b32_e64 v170, v170, v171, s[0:1]
	v_ashrrev_i32_e32 v171, 31, v170
	v_lshlrev_b64 v[170:171], 10, v[170:171]
	v_readfirstlane_b32 s81, v172
	v_lshl_add_u64 v[170:171], v[98:99], 0, v[170:171]
	s_mov_b32 m0, s81
	v_add_u32_e32 v174, 0xc800, v169
	global_load_lds_dwordx4 v[170:171], off
	v_sub_u32_e32 v170, s75, v113
	v_add_u32_e32 v171, s74, v113
	v_cndmask_b32_e64 v170, v170, v171, s[0:1]
	v_ashrrev_i32_e32 v171, 31, v170
	v_lshlrev_b64 v[170:171], 10, v[170:171]
	v_or_b32_e32 v171, v171, v103
	v_or_b32_e32 v170, v170, v102
	v_readfirstlane_b32 s81, v174
	v_lshl_add_u64 v[172:173], s[64:65], 0, v[170:171]
	s_mov_b32 m0, s81
	v_lshl_add_u64 v[170:171], s[72:73], 0, v[170:171]
	global_load_lds_dwordx4 v[172:173], off
	v_add_u32_e32 v172, 0xd000, v169
	v_add_u32_e32 v174, 0xcc00, v169
	v_readfirstlane_b32 s81, v172
	s_mov_b32 m0, s81
	v_add_u32_e32 v169, 0xd400, v169
	global_load_lds_dwordx4 v[170:171], off
	v_sub_u32_e32 v170, s75, v114
	v_add_u32_e32 v171, s74, v114
	v_cndmask_b32_e64 v170, v170, v171, s[0:1]
	v_ashrrev_i32_e32 v171, 31, v170
	v_lshlrev_b64 v[170:171], 10, v[170:171]
	v_or_b32_e32 v171, v171, v103
	v_or_b32_e32 v170, v170, v102
	v_readfirstlane_b32 s74, v174
	v_lshl_add_u64 v[172:173], s[64:65], 0, v[170:171]
	s_mov_b32 m0, s74
	v_readfirstlane_b32 s74, v169
	global_load_lds_dwordx4 v[172:173], off
	v_lshl_add_u64 v[170:171], s[72:73], 0, v[170:171]
	s_mov_b32 m0, s74
	s_nop 0
	global_load_lds_dwordx4 v[170:171], off

; #define MFMA32(a, b, c) __builtin_amdgcn_mfma_f32_32x32x16_bf16((a), (b), (c), 0, 0, 0)
; DI u32 pack2bf(float lo, float hi) { f32x2 v = {lo, hi}; return __builtin_bit_cast(u32, __builtin_convertvector(v, bf2_t)); }
; DI int crow(int i, int h) { return (i & 3) + 8 * (i >> 2) + 4 * h; }
; template <int PASS>
; DI void hgrn_unit(const Params& p, int layer, int unit, char* smem) {
;     ...
;   const int d = tid & 127, half = tid >> 7;
;   const u16* gq = (const u16*)(p.ws + WS_HQ) + hd * 128;
;   const u16* gg = (const u16*)(p.ws + (dir ? WS_GB : WS_GF)) + hd * 128;
;   const u16* gv = (const u16*)(p.ws + WS_HV) + hd * 128;
;   u16* od = (u16*)(p.ws + (dir ? WS_OB : WS_OF));
;   u16* sQm = (u16*)(smem + H_QM); u16* sKm = (u16*)(smem + H_KM); u16* sQb = (u16*)(smem + H_QB);
;   u16* sKlT = (u16*)(smem + H_KLT); u16* sVt = (u16*)(smem + H_VT);
;   float* sDec = (float*)(smem + H_DEC);
;   float* HF = (float*)(p.ws + WS_HF); float* HD = (float*)(p.ws + WS_HD);
;   u32* cnt = (u32*)(p.ws + WS_MISC) + MISC_HCNT + layer * 40 + seq * 8 + grp;
;   f32x16 S[4];
; #pragma unroll
;   for (int b = 0; b < 4; ++b)
; #pragma unroll
;     for (int i = 0; i < 16; ++i) S[b][i] = 0.f;
;   auto chunk_t0 = [&](int c) { return seq_start + (dir ? (nch - 1 - c) : c) * 32; };
;   char* rawW = smem + H_RAW + w * 8192;
;   const int dcol = (w & 1) * 64;
;     ...
;       for (int i = 0; i < 16; ++i) if (crow(i, h) > r) at[i] = 0.f;
; #pragma unroll
;       for (int db = 0; db < 4; ++db)
; #pragma unroll
;         for (int s2 = 0; s2 < 2; ++s2) {
;           bf16x8 a = pack8(S[db], s2);
;           s16x4 lo = *(const s16x4*)(sQb + r * HS + db * 32 + s2 * 16 + 4 * h);
;           s16x4 hi = *(const s16x4*)(sQb + r * HS + db * 32 + s2 * 16 + 8 + 4 * h);
;           oT = MFMA32(a, cat44(lo, hi), oT);
;         }
; #pragma unroll
;       for (int ks = 0; ks < 2; ++ks) {
;         s16x4 lo = *(const s16x4*)(sVt + (32 * w + r) * VS + 16 * ks + 4 * h);
;         s16x4 hi = *(const s16x4*)(sVt + (32 * w + r) * VS + 16 * ks + 8 + 4 * h);
;         oT = MFMA32(cat44(lo, hi), pack8(at, ks), oT);
;       }
;       int tok = dir ? t0 + 31 - r : t0 + r;
; #pragma unroll
;       for (int g = 0; g < 4; ++g) {
;         u32x2 pk = {pack2bf(oT[4 * g], oT[4 * g + 1]), pack2bf(oT[4 * g + 2], oT[4 * g + 3])};
;         *(u32x2*)(od + (size_t)tok * 512 + hd * 128 + 32 * w + 8 * g + 4 * h) = pk;
.LBB0_1346:
	s_and_b64 s[8:9], s[0:1], exec
	s_mov_b32 s8, 0xd800000
	s_cselect_b32 s8, s8, 0x10800000
	s_add_u32 s8, s70, s8
	s_addc_u32 s9, s71, 0
	s_add_i32 s79, s76, 0x80
	s_add_u32 s6, s6, s2
	s_addc_u32 s7, s7, 0
	v_lshlrev_b32_e32 v64, 1, v98
	v_mov_b32_e32 v65, v97
	s_add_u32 s2, s8, s4
	v_and_b32_e32 v66, 31, v100
	v_lshl_add_u64 v[98:99], s[6:7], 0, v[64:65]
	s_addc_u32 s8, s9, s5
	s_lshl_b32 s6, s12, 5
	v_or_b32_e32 v65, s6, v66
	s_movk_i32 s7, 0x50
	v_mul_lo_u32 v65, v65, s7
	s_ashr_i32 s7, s6, 31
	s_lshl_b64 s[6:7], s[6:7], 1
	s_add_u32 s6, s2, s6
	s_movk_i32 s2, 0x880
	v_and_b32_e32 v67, 0x7f, v100
	s_movk_i32 s4, 0x80
	v_mul_lo_u32 v68, v117, s2
	v_cmp_gt_u32_e64 s[42:43], s4, v100
	s_movk_i32 s4, 0x7f
	v_mul_u32_u24_e32 v64, 40, v67
	v_lshlrev_b32_e32 v105, 2, v67
	s_addc_u32 s7, s8, s7
	v_or_b32_e32 v67, v68, v67
	v_cmp_lt_u32_e64 s[4:5], s4, v100
	v_lshl_add_u64 v[100:101], v[96:97], 1, s[6:7]
	v_cmp_eq_u32_e64 s[6:7], 1, v117
	v_lshlrev_b32_e32 v117, 1, v67
	v_or_b32_e32 v67, 2, v96
	v_cmp_gt_u32_e64 s[12:13], v67, v66
	v_or_b32_e32 v67, 3, v96
	v_cmp_gt_u32_e64 s[14:15], v67, v66
	v_or_b32_e32 v67, 8, v96
	v_cmp_gt_u32_e64 s[16:17], v67, v66
	v_or_b32_e32 v67, 9, v96
	v_cmp_gt_u32_e64 s[18:19], v67, v66
	v_or_b32_e32 v67, 10, v96
	v_cmp_gt_u32_e64 s[20:21], v67, v66
	v_or_b32_e32 v67, 11, v96
	v_cmp_gt_u32_e64 s[22:23], v67, v66
	v_or_b32_e32 v67, 16, v96
	v_cmp_gt_u32_e64 s[24:25], v67, v66
	v_or_b32_e32 v67, 17, v96
	v_cmp_gt_u32_e64 s[26:27], v67, v66
	v_or_b32_e32 v67, 18, v96
	v_cmp_gt_u32_e64 s[28:29], v67, v66
	v_or_b32_e32 v67, 19, v96
	v_lshlrev_b32_e32 v64, 1, v64
	v_cmp_gt_u32_e64 s[30:31], v67, v66
	v_or_b32_e32 v67, 24, v96
	v_lshl_add_u32 v104, v115, 1, v64
	v_mul_u32_u24_e32 v64, 0x88, v66
	v_cmp_gt_u32_e64 s[34:35], v67, v66
	v_or_b32_e32 v67, 25, v96
	v_lshlrev_b32_e32 v64, 1, v64
	v_lshlrev_b32_e32 v106, 4, v118
	v_cmp_gt_u32_e64 s[36:37], v67, v66
	v_or_b32_e32 v67, 26, v96
	v_lshlrev_b32_e32 v68, 1, v96
	v_mov_b32_e32 v103, v97
	v_add_u32_e32 v107, v64, v106
	v_cmp_gt_u32_e64 s[8:9], v96, v66
	v_cmp_lt_u32_e64 s[10:11], v96, v66
	v_cmp_gt_u32_e64 s[38:39], v67, v66
	v_or_b32_e32 v67, 27, v96
	v_add_u32_e32 v96, v64, v68
	v_mul_u32_u24_e32 v64, 0x50, v66
	s_sub_i32 s2, s72, s76
	s_mov_b32 s78, 0
	v_add_u32_e32 v115, v65, v106
	v_lshl_add_u32 v116, v116, 1, s77
	v_cmp_gt_u32_e64 s[40:41], v67, v66
	v_add_u32_e32 v118, v65, v68
	v_or_b32_e32 v119, s67, v66
	s_add_i32 s2, s2, -2
	v_lshlrev_b64 v[102:103], 1, v[102:103]
	v_add_u32_e32 v120, v106, v64
	s_waitcnt vmcnt(0)
	s_branch .LBB0_1348

; DI float h2f(u16 b) { return (float)__builtin_bit_cast(_Float16, b); }
; template <int PASS>
; DI void hgrn_unit(const Params& p, int layer, int unit, char* smem) {
;     ...
;   auto gl = [&](int c) {
;     const int t0 = chunk_t0(c);
;     const int row8 = lane >> 3, ch = lane & 7;
; #pragma unroll
;     for (int i = 0; i < 4; ++i) {
;       int j = 8 * i + row8;
;       size_t off = (size_t)(dir ? t0 + 31 - j : t0 + j) * 512 + dcol + ch * 8;
;       __builtin_amdgcn_global_load_lds((const unsigned*)(gg + off), (unsigned*)(rawW + i * 1024 + lane * 16), 16, 0, 0);
;     }
; #pragma unroll
;     for (int i = 0; i < 2; ++i) {
;       int j = half * 16 + 8 * i + row8;
;       size_t off = (size_t)(dir ? t0 + 31 - j : t0 + j) * 512 + dcol + ch * 8;
;       if (PASS == 2) __builtin_amdgcn_global_load_lds((const unsigned*)(gq + off), (unsigned*)(rawW + 4096 + i * 1024 + lane * 16), 16, 0, 0);
;       __builtin_amdgcn_global_load_lds((const unsigned*)(gv + off), (unsigned*)(rawW + 6144 + i * 1024 + lane * 16), 16, 0, 0);
;     }
;   };
;     ...
;   for (int c = c_begin; c < c_end; ++c) {
;     const int t0 = chunk_t0(c);
;     asm volatile("s_waitcnt vmcnt(0)" ::: "memory");
;     const u16* rG = (const u16*)rawW; const u16* rQ = rG + 2048; const u16* rV = rG + 3072;
;     float tot0 = 0.f, tot1 = 0.f, g16;
;     float gval[16]; u16 qraw[16], vraw[16];
; #pragma unroll
;     for (int j = 0; j < 32; ++j) {
;       float g = h2f(rG[j * 64 + lane]);
;       if (j < 16) tot0 += g; else tot1 += g;
;       if (j == 16) g16 = g;
;       if ((j >> 4) == half) gval[j & 15] = g;
;     }
; #pragma unroll
;     for (int jj = 0; jj < 16; ++jj) { if (PASS == 2) qraw[jj] = rQ[jj * 64 + lane]; vraw[jj] = rV[jj * 64 + lane]; }
;     asm volatile("s_waitcnt lgkmcnt(0)" ::: "memory");
;     __builtin_amdgcn_sched_barrier(0);
;     if (c + 1 < c_end) gl(c + 1);
.LBB0_1348:
	s_waitcnt vmcnt(4)
	ds_read_u16 v168, v116 offset:47104
	ds_read_u16 v167, v116 offset:47232
	ds_read_u16 v166, v116 offset:47360
	ds_read_u16 v165, v116 offset:47488
	ds_read_u16 v164, v116 offset:47616
	ds_read_u16 v163, v116 offset:47744
	ds_read_u16 v162, v116 offset:47872
	ds_read_u16 v161, v116 offset:48000
	ds_read_u16 v160, v116 offset:48128
	ds_read_u16 v159, v116 offset:48256
	ds_read_u16 v158, v116 offset:48384
	ds_read_u16 v157, v116 offset:48512
	ds_read_u16 v156, v116 offset:48640
	ds_read_u16 v155, v116 offset:48768
	ds_read_u16 v154, v116 offset:48896
	ds_read_u16 v153, v116 offset:49024
	ds_read_u16 v152, v116 offset:49152
	ds_read_u16 v151, v116 offset:49280
	ds_read_u16 v150, v116 offset:49408
	ds_read_u16 v149, v116 offset:49536
	ds_read_u16 v148, v116 offset:49664
	ds_read_u16 v147, v116 offset:49792
	ds_read_u16 v146, v116 offset:49920
	ds_read_u16 v145, v116 offset:50048
	ds_read_u16 v144, v116 offset:50176
	ds_read_u16 v94, v116 offset:50304
	ds_read_u16 v93, v116 offset:50432
	ds_read_u16 v92, v116 offset:50560
	ds_read_u16 v71, v116 offset:50688
	ds_read_u16 v66, v116 offset:50816
	ds_read_u16 v65, v116 offset:50944
	ds_read_u16 v64, v116 offset:51072
	ds_read_u16 v90, v116 offset:51200
	ds_read_u16 v72, v116 offset:51328
	ds_read_u16 v89, v116 offset:51456
	ds_read_u16 v73, v116 offset:51584
	ds_read_u16 v88, v116 offset:51712
	ds_read_u16 v74, v116 offset:51840
	ds_read_u16 v87, v116 offset:51968
	ds_read_u16 v75, v116 offset:52096
	ds_read_u16 v67, v116 offset:53248
	ds_read_u16 v76, v116 offset:53376
	ds_read_u16 v68, v116 offset:53504
	ds_read_u16 v77, v116 offset:53632
	ds_read_u16 v69, v116 offset:53760
	ds_read_u16 v78, v116 offset:53888
	ds_read_u16 v70, v116 offset:54016
	ds_read_u16 v91, v116 offset:54144
	ds_read_u16 v86, v116 offset:52224
	ds_read_u16 v85, v116 offset:52352
	ds_read_u16 v84, v116 offset:52480
	ds_read_u16 v83, v116 offset:52608
	ds_read_u16 v82, v116 offset:52736
	ds_read_u16 v81, v116 offset:52864
	ds_read_u16 v80, v116 offset:52992
	ds_read_u16 v79, v116 offset:53120
	ds_read_u16 v95, v116 offset:54272
	ds_read_u16 v140, v116 offset:54400
	ds_read_u16 v137, v116 offset:54528
	ds_read_u16 v141, v116 offset:54656
	ds_read_u16 v138, v116 offset:54784
	ds_read_u16 v142, v116 offset:54912
	ds_read_u16 v139, v116 offset:55040
	ds_read_u16 v143, v116 offset:55168
	s_waitcnt lgkmcnt(0)
	s_add_i32 s80, s76, s78
	s_add_i32 s74, s80, 1
	s_cmp_lt_u32 s74, s79
	s_cselect_b64 s[72:73], -1, 0
	s_cmp_ge_u32 s74, s79
	s_cbranch_scc1 .LBB0_1350
	s_and_b64 s[82:83], s[0:1], exec
	s_cselect_b32 s74, s74, s2
	s_lshl_b32 s74, s74, 5
	s_add_i32 s74, s74, s67
	s_or_b32 s75, s74, 31
	v_sub_u32_e32 v169, s75, v108
	v_or_b32_e32 v170, s74, v108
	v_cndmask_b32_e64 v170, v169, v170, s[0:1]
	v_add_u32_e32 v169, s77, v109
	v_ashrrev_i32_e32 v171, 31, v170
	v_add_u32_e32 v172, 0xb800, v169
	v_lshlrev_b64 v[170:171], 10, v[170:171]
	v_readfirstlane_b32 s81, v172
	v_lshl_add_u64 v[170:171], v[98:99], 0, v[170:171]
	s_mov_b32 m0, s81
	v_add_u32_e32 v172, 0xbc00, v169
	global_load_lds_dwordx4 v[170:171], off
	v_sub_u32_e32 v170, s75, v110
	v_or_b32_e32 v171, s74, v110
	v_cndmask_b32_e64 v170, v170, v171, s[0:1]
	v_ashrrev_i32_e32 v171, 31, v170
	v_lshlrev_b64 v[170:171], 10, v[170:171]
	v_readfirstlane_b32 s81, v172
	v_lshl_add_u64 v[170:171], v[98:99], 0, v[170:171]
	s_mov_b32 m0, s81
	v_add_u32_e32 v172, 0xc000, v169
	global_load_lds_dwordx4 v[170:171], off
	v_sub_u32_e32 v170, s75, v111
	v_or_b32_e32 v171, s74, v111
	v_cndmask_b32_e64 v170, v170, v171, s[0:1]
	v_ashrrev_i32_e32 v171, 31, v170
	v_lshlrev_b64 v[170:171], 10, v[170:171]
	v_readfirstlane_b32 s81, v172
	v_lshl_add_u64 v[170:171], v[98:99], 0, v[170:171]
	s_mov_b32 m0, s81
	v_add_u32_e32 v172, 0xc400, v169
	global_load_lds_dwordx4 v[170:171], off
	v_sub_u32_e32 v170, s75, v112
	v_or_b32_e32 v171, s74, v112
	v_cndmask_b32_e64 v170, v170, v171, s[0:1]
	v_ashrrev_i32_e32 v171, 31, v170
	v_lshlrev_b64 v[170:171], 10, v[170:171]
	v_readfirstlane_b32 s81, v172
	v_lshl_add_u64 v[170:171], v[98:99], 0, v[170:171]
	s_mov_b32 m0, s81
	v_add_u32_e32 v174, 0xc800, v169
	global_load_lds_dwordx4 v[170:171], off
	v_sub_u32_e32 v170, s75, v113
	v_add_u32_e32 v171, s74, v113
	v_cndmask_b32_e64 v170, v170, v171, s[0:1]
	v_ashrrev_i32_e32 v171, 31, v170
	v_lshlrev_b64 v[170:171], 10, v[170:171]
	v_or_b32_e32 v171, v171, v103
	v_or_b32_e32 v170, v170, v102
	v_readfirstlane_b32 s81, v174
	v_lshl_add_u64 v[172:173], s[60:61], 0, v[170:171]
	s_mov_b32 m0, s81
	v_lshl_add_u64 v[170:171], s[64:65], 0, v[170:171]
	global_load_lds_dwordx4 v[172:173], off
	v_add_u32_e32 v172, 0xd000, v169
	v_add_u32_e32 v174, 0xcc00, v169
	v_readfirstlane_b32 s81, v172
	s_mov_b32 m0, s81
	v_add_u32_e32 v169, 0xd400, v169
	global_load_lds_dwordx4 v[170:171], off
	v_sub_u32_e32 v170, s75, v114
	v_add_u32_e32 v171, s74, v114
	v_cndmask_b32_e64 v170, v170, v171, s[0:1]
	v_ashrrev_i32_e32 v171, 31, v170
	v_lshlrev_b64 v[170:171], 10, v[170:171]
	v_or_b32_e32 v171, v171, v103
	v_or_b32_e32 v170, v170, v102
	v_readfirstlane_b32 s74, v174
	v_lshl_add_u64 v[172:173], s[60:61], 0, v[170:171]
	s_mov_b32 m0, s74
	v_readfirstlane_b32 s74, v169
	global_load_lds_dwordx4 v[172:173], off
	v_lshl_add_u64 v[170:171], s[64:65], 0, v[170:171]
	s_mov_b32 m0, s74
	s_nop 0
	global_load_lds_dwordx4 v[170:171], off
